# P9 K/V/Q block loads (read once) carry the nt streaming hint; on top of nt hgrn_scan SL loads, write-through GEMM tile stores without barrier write-back (P1,P5,P6,P11,P12), flat barrier release
# baseline (speedup 1.0000x reference)
; #define LAS __attribute__((address_space(3)))
; #define WG_BAR() asm volatile("s_waitcnt lgkmcnt(0)\n\ts_barrier" ::: "memory")
; #define ATT_ADV(ui, s) do { ++(s); if ((s) >= att_unit_steps(F.bid + (ui) * F.G)) { (s) = 0; ++(ui); } } while (0)
; __device__ __forceinline__ bool att_step(int bid, int G, int ui, int s, int& grp, int& h, int& seq, int& blk, bool& comp) {
;     const int unit = bid + ui * G; if (unit >= 768) return false;
;     grp = unit >> 8; const int ul = unit & 255;
;     if (grp < 2) { const int strip = grp == 0 ? ul >> 2 : ul, qt0 = grp == 0 ? (ul & 3) * 8 : 0; h = strip & 15; seq = strip >> 4; blk = qt0 - 1 + s; comp = s > 0; }
;     else { const int strip = ul * 4 + s / 3, ss = s % 3; h = strip & 15; seq = strip >> 4; blk = ss - 1; comp = ss > 0; }
;     return true;
; }
; __device__ __forceinline__ void attn_prompt(Frame& F) {
;     LAS unsigned char* L = F.lds; const int tid = F.tid, lane = F.lane, w = F.wave, r = lane & 15, g4 = lane >> 4;
;     __syncthreads();
;     for (int e = tid; e < 6 * AT_SLOT / 16; e += 512) *(LAS v4u*)(L + e * 16) = (v4u){0u, 0u, 0u, 0u};
;     WG_BAR();
;     const __amdgpu_buffer_rsrc_t wsr = __builtin_amdgcn_make_buffer_rsrc((void*)F.ws, (short)0, (int)WS_END, 0x00020000);
;     v4u kA[2], vA[2], kB[2], vB[2]; bf16x8 qA[2], qB[2];
; #pragma unroll
;     for (int i = 0; i < 2; ++i) { kA[i] = vA[i] = kB[i] = vB[i] = (v4u){0u, 0u, 0u, 0u}; qA[i] = qB[i] = (bf16x8){0, 0, 0, 0, 0, 0, 0, 0}; }
;     int cui = 0, cs = 0, pui = 0, ps = 0, nstep = 0; bool running = true;
;     ATT_LOAD(pui, ps, kA, vA, qA); ATT_ADV(pui, ps);
;     ATT_LOAD(pui, ps, kB, vB, qB); ATT_ADV(pui, ps);
.Lp9n_entry:
	v_readfirstlane_b32 s33, v0
	s_mov_b32 s16, s30
	s_and_b32 s17, s31, 0xffff
	s_mov_b32 s18, 0x2b800000
	s_mov_b32 s19, 0x20000
	s_mov_b32 s95, 0x42400000
	s_lshr_b32 s33, s33, 6
	s_lshl_b32 s33, s33, 4
	v_and_b32_e32 v185, 15, v160
	v_lshrrev_b32_e32 v186, 4, v160
	v_lshlrev_b32_e32 v186, 2, v186
	v_mov_b32_e32 v191, 0xff800000
	v_mul_u32_u24_e32 v170, 0x90, v185
	v_lshl_add_u32 v170, v186, 2, v170
	v_lshrrev_b32_e32 v171, 2, v185
	v_add_u32_e32 v171, v171, v186
	v_mul_u32_u24_e32 v171, 0x90, v171
	v_and_b32_e32 v172, 3, v185
	v_lshl_add_u32 v171, v172, 3, v171
	v_cvt_f32_u32_e32 v172, v186
	v_add_f32_e32 v173, 1.0, v172
	v_add_f32_e32 v174, 2.0, v172
	v_add_f32_e32 v175, 1.0, v174
	v_add_u32_e32 v184, 0, v186
	v_cmp_lt_u32_e32 vcc, v184, v185
	s_nop 1
	v_cndmask_b32_e32 v176, 0, v191, vcc
	v_cmp_gt_u32_e32 vcc, v184, v185
	s_nop 1
	v_cndmask_b32_e32 v180, 0, v191, vcc
	v_add_u32_e32 v184, 1, v186
	v_cmp_lt_u32_e32 vcc, v184, v185
	s_nop 1
	v_cndmask_b32_e32 v177, 0, v191, vcc
	v_cmp_gt_u32_e32 vcc, v184, v185
	s_nop 1
	v_cndmask_b32_e32 v181, 0, v191, vcc
	v_add_u32_e32 v184, 2, v186
	v_cmp_lt_u32_e32 vcc, v184, v185
	s_nop 1
	v_cndmask_b32_e32 v178, 0, v191, vcc
	v_cmp_gt_u32_e32 vcc, v184, v185
	s_nop 1
	v_cndmask_b32_e32 v182, 0, v191, vcc
	v_add_u32_e32 v184, 3, v186
	v_cmp_lt_u32_e32 vcc, v184, v185
	s_nop 1
	v_cndmask_b32_e32 v179, 0, v191, vcc
	v_cmp_gt_u32_e32 vcc, v184, v185
	s_nop 1
	v_cndmask_b32_e32 v183, 0, v191, vcc
	v_add_u32_e32 v184, 0x80, v185
	v_cvt_f32_u32_e32 v184, v184
	v_subrev_u32_e32 v187, 24, v160
	v_min_u32_e32 v187, v160, v187
	v_mul_u32_u24_e32 v187, 0x900, v187
	v_lshlrev_b32_e32 v188, 1, v186
	v_xor_b32_e32 v189, 16, v160
	v_lshlrev_b32_e32 v189, 2, v189
	v_xor_b32_e32 v190, 32, v160
	v_lshlrev_b32_e32 v190, 2, v190
	v_lshrrev_b32_e32 v105, 3, v0
	v_and_b32_e32 v106, 7, v0
	v_mul_u32_u24_e32 v100, 0x90, v105
	v_lshl_add_u32 v100, v106, 4, v100
	v_lshlrev_b32_e32 v101, 4, v0
	v_add_u32_e32 v102, 0x2000, v101
	v_add_u32_e32 v103, s33, v185
	v_lshlrev_b32_e32 v103, 7, v103
	v_lshl_add_u32 v103, v186, 2, v103
	v_mov_b32_e32 v108, 0x80000000
	s_lshr_b32 s21, s2, 2
	s_and_b32 s22, s21, 15
	s_lshr_b32 s23, s21, 4
	s_and_b32 s24, s2, 3
	s_lshl_b32 s24, s24, 3
	s_lshl_b32 s25, s22, 2
	s_lshl_b32 s26, s23, 12
	s_or_b32 s25, s25, s26
	s_lshl_b32 s26, s24, 6
	s_or_b32 s25, s25, s26
	s_cmp_lg_u32 s24, 0
	s_cselect_b32 s26, 0x200000, 0
	s_or_b32 s26, s25, s26
	v_writelane_b32 v104, s26, 0
	s_add_i32 s26, s25, 3145792
	v_writelane_b32 v104, s26, 1
	s_add_i32 s26, s25, 3145856
	v_writelane_b32 v104, s26, 2
	s_add_i32 s26, s25, 3145920
	v_writelane_b32 v104, s26, 3
	s_add_i32 s26, s25, 3145984
	v_writelane_b32 v104, s26, 4
	s_add_i32 s26, s25, 3146048
	v_writelane_b32 v104, s26, 5
	s_add_i32 s26, s25, 3146112
	v_writelane_b32 v104, s26, 6
	s_add_i32 s26, s25, 3146176
	v_writelane_b32 v104, s26, 7
	s_add_i32 s26, s25, 3146240
	v_writelane_b32 v104, s26, 8
	s_and_b32 s22, s2, 15
	s_lshr_b32 s23, s2, 4
	s_lshl_b32 s25, s22, 2
	s_lshl_b32 s26, s23, 12
	s_or_b32 s25, s25, s26
	s_or_b32 s25, s25, 1
	v_writelane_b32 v104, s25, 9
	s_add_i32 s26, s25, 3145792
	v_writelane_b32 v104, s26, 10
	s_add_i32 s26, s25, 3145856
	v_writelane_b32 v104, s26, 11
	s_add_i32 s26, s25, 3145920
	v_writelane_b32 v104, s26, 12
	s_add_i32 s26, s25, 3145984
	v_writelane_b32 v104, s26, 13
	s_add_i32 s26, s25, 3146048
	v_writelane_b32 v104, s26, 14
	s_add_i32 s26, s25, 3146112
	v_writelane_b32 v104, s26, 15
	s_add_i32 s26, s25, 3146176
	v_writelane_b32 v104, s26, 16
	s_add_i32 s26, s25, 3146240
	v_writelane_b32 v104, s26, 17
	s_and_b32 s22, s2, 3
	s_lshl_b32 s22, s22, 2
	s_lshr_b32 s23, s2, 2
	s_lshl_b32 s26, s23, 12
	s_add_i32 s25, s22, 0
	s_lshl_b32 s25, s25, 2
	s_or_b32 s25, s25, s26
	s_or_b32 s25, s25, 2
	v_writelane_b32 v104, s25, 18
	s_add_i32 s27, s25, 3145792
	v_writelane_b32 v104, s27, 19
	s_add_i32 s27, s25, 3145856
	v_writelane_b32 v104, s27, 20
	s_add_i32 s25, s22, 1
	s_lshl_b32 s25, s25, 2
	s_or_b32 s25, s25, s26
	s_or_b32 s25, s25, 2
	v_writelane_b32 v104, s25, 21
	s_add_i32 s27, s25, 3145792
	v_writelane_b32 v104, s27, 22
	s_add_i32 s27, s25, 3145856
	v_writelane_b32 v104, s27, 23
	s_add_i32 s25, s22, 2
	s_lshl_b32 s25, s25, 2
	s_or_b32 s25, s25, s26
	s_or_b32 s25, s25, 2
	v_writelane_b32 v104, s25, 24
	s_add_i32 s27, s25, 3145792
	v_writelane_b32 v104, s27, 25
	s_add_i32 s27, s25, 3145856
	v_writelane_b32 v104, s27, 26
	s_add_i32 s25, s22, 3
	s_lshl_b32 s25, s25, 2
	s_or_b32 s25, s25, s26
	s_or_b32 s25, s25, 2
	v_writelane_b32 v104, s25, 27
	s_add_i32 s27, s25, 3145792
	v_writelane_b32 v104, s27, 28
	s_add_i32 s27, s25, 3145856
	v_writelane_b32 v104, s27, 29
	s_mov_b32 s25, 0
	v_writelane_b32 v104, s25, 30
	v_writelane_b32 v104, s25, 31
	v_writelane_b32 v104, s25, 32
	s_nop 1
	v_readlane_b32 s23, v104, 0
	s_nop 3
	s_bfe_u32 s36, s23, 0x20000
	s_bfe_u32 s37, s23, 0x40002
	s_bfe_u32 s38, s23, 0x60006
	s_bfe_u32 s39, s23, 0x8000c
	s_lshl_b32 s40, s36, 1
	s_lshr_b32 s40, 0x1000, s40
	s_mul_i32 s39, s39, s40
	s_add_i32 s38, s38, -1
	s_lshl_b32 s38, s38, 7
	s_add_i32 s39, s39, s38
	s_lshl_b32 s39, s39, 7
	s_mul_i32 s37, s37, 0x208000
	s_add_i32 s39, s39, s37
	s_bitcmp1_b32 s23, 21
	s_cselect_b32 s39, s39, 0x80000000
	s_mul_i32 s36, s36, 0x2100000
	s_add_i32 s40, s36, 0x16a00000
	s_add_i32 s41, s36, 0x1cd00000
	s_add_i32 s42, s36, 0x10700000
	v_add_u32_e32 v105, s39, v101
	v_add_u32_e32 v106, s39, v102
	v_add_u32_e32 v107, s39, v103
	buffer_load_dwordx4 v[26:29], v105, s[16:19], s40 offen nt
	buffer_load_dwordx4 v[30:33], v105, s[16:19], s41 offen nt
	buffer_load_dwordx4 v[34:37], v106, s[16:19], s40 offen nt
	buffer_load_dwordx4 v[38:41], v106, s[16:19], s41 offen nt
	buffer_load_dwordx4 v[2:5], v107, s[16:19], s42 offen nt
	buffer_load_dwordx4 v[6:9], v107, s[16:19], s42 offen offset:64 nt
	buffer_store_dword v108, v108, s[16:19], 0 offen
	buffer_store_dword v108, v108, s[16:19], 0 offen
	buffer_store_dword v108, v108, s[16:19], 0 offen
	buffer_store_dword v108, v108, s[16:19], 0 offen
	buffer_store_dword v108, v108, s[16:19], 0 offen
	v_readlane_b32 s23, v104, 1
	s_nop 3
	s_bfe_u32 s36, s23, 0x20000
	s_bfe_u32 s37, s23, 0x40002
	s_bfe_u32 s38, s23, 0x60006
	s_bfe_u32 s39, s23, 0x8000c
	s_lshl_b32 s40, s36, 1
	s_lshr_b32 s40, 0x1000, s40
	s_mul_i32 s39, s39, s40
	s_add_i32 s38, s38, -1
	s_lshl_b32 s38, s38, 7
	s_add_i32 s39, s39, s38
	s_lshl_b32 s39, s39, 7
	s_mul_i32 s37, s37, 0x208000
	s_add_i32 s39, s39, s37
	s_bitcmp1_b32 s23, 21
	s_cselect_b32 s39, s39, 0x80000000
	s_mul_i32 s36, s36, 0x2100000
	s_add_i32 s40, s36, 0x16a00000
	s_add_i32 s41, s36, 0x1cd00000
	s_add_i32 s42, s36, 0x10700000
	v_add_u32_e32 v105, s39, v101
	v_add_u32_e32 v106, s39, v102
	v_add_u32_e32 v107, s39, v103
	buffer_load_dwordx4 v[42:45], v105, s[16:19], s40 offen nt
	buffer_load_dwordx4 v[46:49], v105, s[16:19], s41 offen nt
	buffer_load_dwordx4 v[50:53], v106, s[16:19], s40 offen nt
	buffer_load_dwordx4 v[54:57], v106, s[16:19], s41 offen nt
	buffer_load_dwordx4 v[10:13], v107, s[16:19], s42 offen nt
	buffer_load_dwordx4 v[14:17], v107, s[16:19], s42 offen offset:64 nt
	buffer_store_dword v108, v108, s[16:19], 0 offen
	buffer_store_dword v108, v108, s[16:19], 0 offen
	buffer_store_dword v108, v108, s[16:19], 0 offen
	buffer_store_dword v108, v108, s[16:19], 0 offen
	buffer_store_dword v108, v108, s[16:19], 0 offen
	v_readlane_b32 s23, v104, 2
	s_nop 3
	s_bfe_u32 s36, s23, 0x20000
	s_bfe_u32 s37, s23, 0x40002
	s_bfe_u32 s38, s23, 0x60006
	s_bfe_u32 s39, s23, 0x8000c
	s_lshl_b32 s40, s36, 1
	s_lshr_b32 s40, 0x1000, s40
	s_mul_i32 s39, s39, s40
	s_add_i32 s38, s38, -1
	s_lshl_b32 s38, s38, 7
	s_add_i32 s39, s39, s38
	s_lshl_b32 s39, s39, 7
	s_mul_i32 s37, s37, 0x208000
	s_add_i32 s39, s39, s37
	s_bitcmp1_b32 s23, 21
	s_cselect_b32 s39, s39, 0x80000000
	s_mul_i32 s36, s36, 0x2100000
	s_add_i32 s40, s36, 0x16a00000
	s_add_i32 s41, s36, 0x1cd00000
	s_add_i32 s42, s36, 0x10700000
	v_add_u32_e32 v105, s39, v101
	v_add_u32_e32 v106, s39, v102
	v_add_u32_e32 v107, s39, v103
	buffer_load_dwordx4 v[110:113], v105, s[16:19], s40 offen nt
	buffer_load_dwordx4 v[114:117], v105, s[16:19], s41 offen nt
	buffer_load_dwordx4 v[118:121], v106, s[16:19], s40 offen nt
	buffer_load_dwordx4 v[122:125], v106, s[16:19], s41 offen nt
	buffer_load_dwordx4 v[126:129], v107, s[16:19], s42 offen nt
	buffer_load_dwordx4 v[130:133], v107, s[16:19], s42 offen offset:64 nt
	buffer_store_dword v108, v108, s[16:19], 0 offen
	buffer_store_dword v108, v108, s[16:19], 0 offen
	buffer_store_dword v108, v108, s[16:19], 0 offen
	buffer_store_dword v108, v108, s[16:19], 0 offen
	buffer_store_dword v108, v108, s[16:19], 0 offen
	s_mov_b32 s20, 0
	s_mov_b32 s21, 0
	.p2align 6
.Lp9n_loop:
.Lp9n_stepA:
	s_add_i32 s23, s20, 3
	v_readlane_b32 s22, v104, s20
	v_readlane_b32 s23, v104, s23
	s_mul_i32 s24, s21, 0x4800
	s_waitcnt vmcnt(27)
	v_add_u32_e32 v109, s24, v100
	ds_write_b128 v109, v[26:29]
	ds_write_b128 v109, v[30:33] offset:55296
	ds_write_b128 v109, v[34:37] offset:9216
	ds_write_b128 v109, v[38:41] offset:64512
	v_mov_b64_e32 v[18:19], v[2:3]
	v_mov_b64_e32 v[20:21], v[4:5]
	v_mov_b64_e32 v[22:23], v[6:7]
	v_mov_b64_e32 v[24:25], v[8:9]
	s_waitcnt lgkmcnt(0)
	s_barrier
	s_bfe_u32 s36, s23, 0x20000
	s_bfe_u32 s37, s23, 0x40002
	s_bfe_u32 s38, s23, 0x60006
	s_bfe_u32 s39, s23, 0x8000c
	s_lshl_b32 s40, s36, 1
	s_lshr_b32 s40, 0x1000, s40
	s_mul_i32 s39, s39, s40
	s_add_i32 s38, s38, -1
	s_lshl_b32 s38, s38, 7
	s_add_i32 s39, s39, s38
	s_lshl_b32 s39, s39, 7
	s_mul_i32 s37, s37, 0x208000
	s_add_i32 s39, s39, s37
	s_bitcmp1_b32 s23, 21
	s_cselect_b32 s39, s39, 0x80000000
	s_mul_i32 s36, s36, 0x2100000
	s_add_i32 s40, s36, 0x16a00000
	s_add_i32 s41, s36, 0x1cd00000
	s_add_i32 s42, s36, 0x10700000
	v_add_u32_e32 v105, s39, v101
	v_add_u32_e32 v106, s39, v102
	v_add_u32_e32 v107, s39, v103
	s_bitcmp1_b32 s22, 20
	s_cbranch_scc0 .Lp9n_nocompA
	s_and_b32 s99, s22, 63
	s_bfe_u32 s4, s22, 0x60006
	s_add_i32 s4, s4, -1
	s_lshl_b32 s4, s4, 6
	s_or_b32 s99, s99, s4
	s_add_i32 s4, s21, -1
	s_cmp_lt_i32 s4, 0
	s_cselect_b32 s4, 2, s4
	s_lshl_b32 s4, s4, 3
	s_lshr_b32 s5, s33, 4
	s_add_i32 s4, s4, s5
	s_lshl_b32 s4, s4, 11
	s_or_b32 s99, s99, s4
	s_bfe_u32 s4, s22, 0x8000c
	s_lshl_b32 s4, s4, 17
	s_or_b32 s99, s99, s4
	buffer_load_dwordx4 v[26:29], v105, s[16:19], s40 offen nt
	buffer_load_dwordx4 v[30:33], v105, s[16:19], s41 offen nt
	buffer_load_dwordx4 v[34:37], v106, s[16:19], s40 offen nt
	buffer_load_dwordx4 v[38:41], v106, s[16:19], s41 offen nt
	buffer_load_dwordx4 v[2:5], v107, s[16:19], s42 offen nt
	buffer_load_dwordx4 v[6:9], v107, s[16:19], s42 offen offset:64 nt
	s_bitset1_b32 s99, 26
	s_branch .Lat_tile
.Lp9n_nocompA:
	buffer_load_dwordx4 v[26:29], v105, s[16:19], s40 offen nt
	buffer_load_dwordx4 v[30:33], v105, s[16:19], s41 offen nt
	buffer_load_dwordx4 v[34:37], v106, s[16:19], s40 offen nt
	buffer_load_dwordx4 v[38:41], v106, s[16:19], s41 offen nt
	buffer_load_dwordx4 v[2:5], v107, s[16:19], s42 offen nt
	buffer_load_dwordx4 v[6:9], v107, s[16:19], s42 offen offset:64 nt
	buffer_store_dword v108, v108, s[16:19], 0 offen
	buffer_store_dword v108, v108, s[16:19], 0 offen
	buffer_store_dword v108, v108, s[16:19], 0 offen
	buffer_store_dword v108, v108, s[16:19], 0 offen
	buffer_store_dword v108, v108, s[16:19], 0 offen

.Lp9n_stepB:
	s_add_i32 s23, s20, 3
	v_readlane_b32 s22, v104, s20
	v_readlane_b32 s23, v104, s23
	s_mul_i32 s24, s21, 0x4800
	s_waitcnt vmcnt(27)
	v_add_u32_e32 v109, s24, v100
	ds_write_b128 v109, v[42:45]
	ds_write_b128 v109, v[46:49] offset:55296
	ds_write_b128 v109, v[50:53] offset:9216
	ds_write_b128 v109, v[54:57] offset:64512
	v_mov_b64_e32 v[18:19], v[10:11]
	v_mov_b64_e32 v[20:21], v[12:13]
	v_mov_b64_e32 v[22:23], v[14:15]
	v_mov_b64_e32 v[24:25], v[16:17]
	s_waitcnt lgkmcnt(0)
	s_barrier
	s_bfe_u32 s36, s23, 0x20000
	s_bfe_u32 s37, s23, 0x40002
	s_bfe_u32 s38, s23, 0x60006
	s_bfe_u32 s39, s23, 0x8000c
	s_lshl_b32 s40, s36, 1
	s_lshr_b32 s40, 0x1000, s40
	s_mul_i32 s39, s39, s40
	s_add_i32 s38, s38, -1
	s_lshl_b32 s38, s38, 7
	s_add_i32 s39, s39, s38
	s_lshl_b32 s39, s39, 7
	s_mul_i32 s37, s37, 0x208000
	s_add_i32 s39, s39, s37
	s_bitcmp1_b32 s23, 21
	s_cselect_b32 s39, s39, 0x80000000
	s_mul_i32 s36, s36, 0x2100000
	s_add_i32 s40, s36, 0x16a00000
	s_add_i32 s41, s36, 0x1cd00000
	s_add_i32 s42, s36, 0x10700000
	v_add_u32_e32 v105, s39, v101
	v_add_u32_e32 v106, s39, v102
	v_add_u32_e32 v107, s39, v103
	s_bitcmp1_b32 s22, 20
	s_cbranch_scc0 .Lp9n_nocompB
	s_and_b32 s99, s22, 63
	s_bfe_u32 s4, s22, 0x60006
	s_add_i32 s4, s4, -1
	s_lshl_b32 s4, s4, 6
	s_or_b32 s99, s99, s4
	s_add_i32 s4, s21, -1
	s_cmp_lt_i32 s4, 0
	s_cselect_b32 s4, 2, s4
	s_lshl_b32 s4, s4, 3
	s_lshr_b32 s5, s33, 4
	s_add_i32 s4, s4, s5
	s_lshl_b32 s4, s4, 11
	s_or_b32 s99, s99, s4
	s_bfe_u32 s4, s22, 0x8000c
	s_lshl_b32 s4, s4, 17
	s_or_b32 s99, s99, s4
	buffer_load_dwordx4 v[42:45], v105, s[16:19], s40 offen nt
	buffer_load_dwordx4 v[46:49], v105, s[16:19], s41 offen nt
	buffer_load_dwordx4 v[50:53], v106, s[16:19], s40 offen nt
	buffer_load_dwordx4 v[54:57], v106, s[16:19], s41 offen nt
	buffer_load_dwordx4 v[10:13], v107, s[16:19], s42 offen nt
	buffer_load_dwordx4 v[14:17], v107, s[16:19], s42 offen offset:64 nt
	s_bitset1_b32 s99, 27
	s_branch .Lat_tile
.Lp9n_nocompB:
	buffer_load_dwordx4 v[42:45], v105, s[16:19], s40 offen nt
	buffer_load_dwordx4 v[46:49], v105, s[16:19], s41 offen nt
	buffer_load_dwordx4 v[50:53], v106, s[16:19], s40 offen nt
	buffer_load_dwordx4 v[54:57], v106, s[16:19], s41 offen nt
	buffer_load_dwordx4 v[10:13], v107, s[16:19], s42 offen nt
	buffer_load_dwordx4 v[14:17], v107, s[16:19], s42 offen offset:64 nt
	buffer_store_dword v108, v108, s[16:19], 0 offen
	buffer_store_dword v108, v108, s[16:19], 0 offen
	buffer_store_dword v108, v108, s[16:19], 0 offen
	buffer_store_dword v108, v108, s[16:19], 0 offen
	buffer_store_dword v108, v108, s[16:19], 0 offen

.Lp9n_stepC:
	s_add_i32 s23, s20, 3
	v_readlane_b32 s22, v104, s20
	v_readlane_b32 s23, v104, s23
	s_mul_i32 s24, s21, 0x4800
	s_waitcnt vmcnt(27)
	v_add_u32_e32 v109, s24, v100
	ds_write_b128 v109, v[110:113]
	ds_write_b128 v109, v[114:117] offset:55296
	ds_write_b128 v109, v[118:121] offset:9216
	ds_write_b128 v109, v[122:125] offset:64512
	v_mov_b64_e32 v[18:19], v[126:127]
	v_mov_b64_e32 v[20:21], v[128:129]
	v_mov_b64_e32 v[22:23], v[130:131]
	v_mov_b64_e32 v[24:25], v[132:133]
	s_waitcnt lgkmcnt(0)
	s_barrier
	s_bfe_u32 s36, s23, 0x20000
	s_bfe_u32 s37, s23, 0x40002
	s_bfe_u32 s38, s23, 0x60006
	s_bfe_u32 s39, s23, 0x8000c
	s_lshl_b32 s40, s36, 1
	s_lshr_b32 s40, 0x1000, s40
	s_mul_i32 s39, s39, s40
	s_add_i32 s38, s38, -1
	s_lshl_b32 s38, s38, 7
	s_add_i32 s39, s39, s38
	s_lshl_b32 s39, s39, 7
	s_mul_i32 s37, s37, 0x208000
	s_add_i32 s39, s39, s37
	s_bitcmp1_b32 s23, 21
	s_cselect_b32 s39, s39, 0x80000000
	s_mul_i32 s36, s36, 0x2100000
	s_add_i32 s40, s36, 0x16a00000
	s_add_i32 s41, s36, 0x1cd00000
	s_add_i32 s42, s36, 0x10700000
	v_add_u32_e32 v105, s39, v101
	v_add_u32_e32 v106, s39, v102
	v_add_u32_e32 v107, s39, v103
	s_bitcmp1_b32 s22, 20
	s_cbranch_scc0 .Lp9n_nocompC
	s_and_b32 s99, s22, 63
	s_bfe_u32 s4, s22, 0x60006
	s_add_i32 s4, s4, -1
	s_lshl_b32 s4, s4, 6
	s_or_b32 s99, s99, s4
	s_add_i32 s4, s21, -1
	s_cmp_lt_i32 s4, 0
	s_cselect_b32 s4, 2, s4
	s_lshl_b32 s4, s4, 3
	s_lshr_b32 s5, s33, 4
	s_add_i32 s4, s4, s5
	s_lshl_b32 s4, s4, 11
	s_or_b32 s99, s99, s4
	s_bfe_u32 s4, s22, 0x8000c
	s_lshl_b32 s4, s4, 17
	s_or_b32 s99, s99, s4
	buffer_load_dwordx4 v[110:113], v105, s[16:19], s40 offen nt
	buffer_load_dwordx4 v[114:117], v105, s[16:19], s41 offen nt
	buffer_load_dwordx4 v[118:121], v106, s[16:19], s40 offen nt
	buffer_load_dwordx4 v[122:125], v106, s[16:19], s41 offen nt
	buffer_load_dwordx4 v[126:129], v107, s[16:19], s42 offen nt
	buffer_load_dwordx4 v[130:133], v107, s[16:19], s42 offen offset:64 nt
	s_bitset1_b32 s99, 28
	s_branch .Lat_tile
.Lp9n_nocompC:
	buffer_load_dwordx4 v[110:113], v105, s[16:19], s40 offen nt
	buffer_load_dwordx4 v[114:117], v105, s[16:19], s41 offen nt
	buffer_load_dwordx4 v[118:121], v106, s[16:19], s40 offen nt
	buffer_load_dwordx4 v[122:125], v106, s[16:19], s41 offen nt
	buffer_load_dwordx4 v[126:129], v107, s[16:19], s42 offen nt
	buffer_load_dwordx4 v[130:133], v107, s[16:19], s42 offen offset:64 nt
	buffer_store_dword v108, v108, s[16:19], 0 offen
	buffer_store_dword v108, v108, s[16:19], 0 offen
	buffer_store_dword v108, v108, s[16:19], 0 offen
	buffer_store_dword v108, v108, s[16:19], 0 offen
	buffer_store_dword v108, v108, s[16:19], 0 offen
